# select search: first key segment counted last with scalar popcounts while the cross-lane reduction of the per-lane counts runs underneath
# speedup vs baseline: 1.0094x; 1.0002x over previous
; __device__ __forceinline__ int count_ge(const unsigned (&u)[64], unsigned cand, int nblk) {
;     int c0 = 0, c1 = 0;
;     const unsigned ts = __builtin_amdgcn_readfirstlane(cand);
; #pragma unroll
;     for (int B = 0; B < 2; ++B) {
;         if (B < nblk) {
; #pragma unroll
;             for (int i = 0; i < 32; i += 4) CNT4(c0, c1, ts, u[B * 32 + i], u[B * 32 + i + 1], u[B * 32 + i + 2], u[B * 32 + i + 3]);
;         }
;     }
.Lsqa_count:
	v_mov_b32_e32 v0, 0
	v_mov_b32_e32 v34, 0
	s_cmp_eq_u32 s32, 1
	s_cbranch_scc1 .Lsqa_red
	v_cmp_le_u32_e64 s[4:5], s14, v144
	v_cmp_le_u32_e64 s[6:7], s14, v148
	v_cmp_le_u32_e64 s[10:11], s14, v145
	v_cmp_le_u32_e64 s[26:27], s14, v149
	v_addc_co_u32_e64 v0, s[28:29], 0, v0, s[4:5]
	v_addc_co_u32_e64 v34, s[30:31], 0, v34, s[6:7]
	v_addc_co_u32_e64 v0, s[28:29], 0, v0, s[10:11]
	v_addc_co_u32_e64 v34, s[30:31], 0, v34, s[26:27]
	v_cmp_le_u32_e64 s[4:5], s14, v150
	v_cmp_le_u32_e64 s[6:7], s14, v152
	v_cmp_le_u32_e64 s[10:11], s14, v151
	v_cmp_le_u32_e64 s[26:27], s14, v154
	v_addc_co_u32_e64 v0, s[28:29], 0, v0, s[4:5]
	v_addc_co_u32_e64 v34, s[30:31], 0, v34, s[6:7]
	v_addc_co_u32_e64 v0, s[28:29], 0, v0, s[10:11]
	v_addc_co_u32_e64 v34, s[30:31], 0, v34, s[26:27]
	s_cmp_eq_u32 s32, 2
	s_cbranch_scc1 .Lsqa_red
	v_cmp_le_u32_e64 s[4:5], s14, v153
	v_cmp_le_u32_e64 s[6:7], s14, v156
	v_cmp_le_u32_e64 s[10:11], s14, v155
	v_cmp_le_u32_e64 s[26:27], s14, v157
	v_addc_co_u32_e64 v0, s[28:29], 0, v0, s[4:5]
	v_addc_co_u32_e64 v34, s[30:31], 0, v34, s[6:7]
	v_addc_co_u32_e64 v0, s[28:29], 0, v0, s[10:11]
	v_addc_co_u32_e64 v34, s[30:31], 0, v34, s[26:27]
	v_cmp_le_u32_e64 s[4:5], s14, v158
	v_cmp_le_u32_e64 s[6:7], s14, v160
	v_cmp_le_u32_e64 s[10:11], s14, v159
	v_cmp_le_u32_e64 s[26:27], s14, v161
	v_addc_co_u32_e64 v0, s[28:29], 0, v0, s[4:5]
	v_addc_co_u32_e64 v34, s[30:31], 0, v34, s[6:7]
	v_addc_co_u32_e64 v0, s[28:29], 0, v0, s[10:11]
	v_addc_co_u32_e64 v34, s[30:31], 0, v34, s[26:27]
	v_cmp_le_u32_e64 s[4:5], s14, v167
	v_cmp_le_u32_e64 s[6:7], s14, v169
	v_cmp_le_u32_e64 s[10:11], s14, v168
	v_cmp_le_u32_e64 s[26:27], s14, v170
	v_addc_co_u32_e64 v0, s[28:29], 0, v0, s[4:5]
	v_addc_co_u32_e64 v34, s[30:31], 0, v34, s[6:7]
	v_addc_co_u32_e64 v0, s[28:29], 0, v0, s[10:11]
	v_addc_co_u32_e64 v34, s[30:31], 0, v34, s[26:27]
	v_cmp_le_u32_e64 s[4:5], s14, v173
	v_cmp_le_u32_e64 s[6:7], s14, v174
	v_cmp_le_u32_e64 s[10:11], s14, v175
	v_cmp_le_u32_e64 s[26:27], s14, v176
	v_addc_co_u32_e64 v0, s[28:29], 0, v0, s[4:5]
	v_addc_co_u32_e64 v34, s[30:31], 0, v34, s[6:7]
	v_addc_co_u32_e64 v0, s[28:29], 0, v0, s[10:11]
	v_addc_co_u32_e64 v34, s[30:31], 0, v34, s[26:27]
	s_cmp_eq_u32 s32, 3
	s_cbranch_scc1 .Lsqa_red
	v_cmp_le_u32_e64 s[4:5], s14, v76
	v_cmp_le_u32_e64 s[6:7], s14, v78
	v_cmp_le_u32_e64 s[10:11], s14, v77
	v_cmp_le_u32_e64 s[26:27], s14, v79
	v_addc_co_u32_e64 v0, s[28:29], 0, v0, s[4:5]
	v_addc_co_u32_e64 v34, s[30:31], 0, v34, s[6:7]
	v_addc_co_u32_e64 v0, s[28:29], 0, v0, s[10:11]
	v_addc_co_u32_e64 v34, s[30:31], 0, v34, s[26:27]
	v_cmp_le_u32_e64 s[4:5], s14, v80
	v_cmp_le_u32_e64 s[6:7], s14, v84
	v_cmp_le_u32_e64 s[10:11], s14, v81
	v_cmp_le_u32_e64 s[26:27], s14, v85
	v_addc_co_u32_e64 v0, s[28:29], 0, v0, s[4:5]
	v_addc_co_u32_e64 v34, s[30:31], 0, v34, s[6:7]
	v_addc_co_u32_e64 v0, s[28:29], 0, v0, s[10:11]
	v_addc_co_u32_e64 v34, s[30:31], 0, v34, s[26:27]
	s_cmp_eq_u32 s32, 4
	s_cbranch_scc1 .Lsqa_red
	v_cmp_le_u32_e64 s[4:5], s14, v82
	v_cmp_le_u32_e64 s[6:7], s14, v86
	v_cmp_le_u32_e64 s[10:11], s14, v83
	v_cmp_le_u32_e64 s[26:27], s14, v87
	v_addc_co_u32_e64 v0, s[28:29], 0, v0, s[4:5]
	v_addc_co_u32_e64 v34, s[30:31], 0, v34, s[6:7]
	v_addc_co_u32_e64 v0, s[28:29], 0, v0, s[10:11]
	v_addc_co_u32_e64 v34, s[30:31], 0, v34, s[26:27]
	v_cmp_le_u32_e64 s[4:5], s14, v89
	v_cmp_le_u32_e64 s[6:7], s14, v91
	v_cmp_le_u32_e64 s[10:11], s14, v90
	v_cmp_le_u32_e64 s[26:27], s14, v93
	v_addc_co_u32_e64 v0, s[28:29], 0, v0, s[4:5]
	v_addc_co_u32_e64 v34, s[30:31], 0, v34, s[6:7]
	v_addc_co_u32_e64 v0, s[28:29], 0, v0, s[10:11]
	v_addc_co_u32_e64 v34, s[30:31], 0, v34, s[26:27]
	s_cmp_eq_u32 s32, 5
	s_cbranch_scc1 .Lsqa_red
	v_cmp_le_u32_e64 s[4:5], s14, v92
	v_cmp_le_u32_e64 s[6:7], s14, v95
	v_cmp_le_u32_e64 s[10:11], s14, v94
	v_cmp_le_u32_e64 s[26:27], s14, v96
	v_addc_co_u32_e64 v0, s[28:29], 0, v0, s[4:5]
	v_addc_co_u32_e64 v34, s[30:31], 0, v34, s[6:7]
	v_addc_co_u32_e64 v0, s[28:29], 0, v0, s[10:11]
	v_addc_co_u32_e64 v34, s[30:31], 0, v34, s[26:27]
	v_cmp_le_u32_e64 s[4:5], s14, v97
	v_cmp_le_u32_e64 s[6:7], s14, v172
	v_cmp_le_u32_e64 s[10:11], s14, v171
	v_cmp_le_u32_e64 s[26:27], s14, v178
	v_addc_co_u32_e64 v0, s[28:29], 0, v0, s[4:5]
	v_addc_co_u32_e64 v34, s[30:31], 0, v34, s[6:7]
	v_addc_co_u32_e64 v0, s[28:29], 0, v0, s[10:11]
	v_addc_co_u32_e64 v34, s[30:31], 0, v34, s[26:27]
	v_cmp_le_u32_e64 s[4:5], s14, v180
	v_cmp_le_u32_e64 s[6:7], s14, v183
	v_cmp_le_u32_e64 s[10:11], s14, v182
	v_cmp_le_u32_e64 s[26:27], s14, v184
	v_addc_co_u32_e64 v0, s[28:29], 0, v0, s[4:5]
	v_addc_co_u32_e64 v34, s[30:31], 0, v34, s[6:7]
	v_addc_co_u32_e64 v0, s[28:29], 0, v0, s[10:11]
	v_addc_co_u32_e64 v34, s[30:31], 0, v34, s[26:27]
	v_cmp_le_u32_e64 s[4:5], s14, v186
	v_cmp_le_u32_e64 s[6:7], s14, v187
	v_cmp_le_u32_e64 s[10:11], s14, v188
	v_cmp_le_u32_e64 s[26:27], s14, v189
	v_addc_co_u32_e64 v0, s[28:29], 0, v0, s[4:5]
	v_addc_co_u32_e64 v34, s[30:31], 0, v34, s[6:7]
	v_addc_co_u32_e64 v0, s[28:29], 0, v0, s[10:11]
	v_addc_co_u32_e64 v34, s[30:31], 0, v34, s[26:27]
; __device__ __forceinline__ int wave_isum(int v) {
;     v += __builtin_amdgcn_update_dpp(0, v, 0x111, 0xf, 0xf, false);
;     v += __builtin_amdgcn_update_dpp(0, v, 0x112, 0xf, 0xf, false);
;     v += __builtin_amdgcn_update_dpp(0, v, 0x114, 0xf, 0xf, false);
;     v += __builtin_amdgcn_update_dpp(0, v, 0x118, 0xf, 0xf, false);
;     v += __builtin_amdgcn_update_dpp(0, v, 0x142, 0xa, 0xf, false);
;     v += __builtin_amdgcn_update_dpp(0, v, 0x143, 0xc, 0xf, false);
;     return __builtin_amdgcn_readlane(v, 63);
; }
; __device__ __forceinline__ void select_query(const unsigned (&u)[64], unsigned vmax, int q, int b, int lane, unsigned* MASKb) {
;     ...
;             const int c = count_ge(u, mid, nblk);
;             if (c == 256) { T = mid; exact = true; break; }
;             if (c > 256) { lo = mid; Llo = __log2f((float)c) - L256; if (last == 1) Lhi *= 0.5f; last = 1; }
;             else { hi = mid; Lhi = L256 - __log2f(fmaxf((float)c, 0.5f)); if (last == 2) Llo *= 0.5f; last = 2; }
.Lsqa_red:
	v_add_u32_e32 v0, v0, v34
	v_cmp_le_u32_e64 s[4:5], s14, v138
	v_cmp_le_u32_e64 s[6:7], s14, v140
	v_add_u32_dpp v0, v0, v0 row_shr:1 row_mask:0xf bank_mask:0xf bound_ctrl:1
	v_cmp_le_u32_e64 s[10:11], s14, v139
	v_cmp_le_u32_e64 s[26:27], s14, v141
	v_add_u32_dpp v0, v0, v0 row_shr:2 row_mask:0xf bank_mask:0xf bound_ctrl:1
	s_bcnt1_i32_b64 s28, s[4:5]
	s_bcnt1_i32_b64 s29, s[6:7]
	v_cmp_le_u32_e64 s[4:5], s14, v142
	v_add_u32_dpp v0, v0, v0 row_shr:4 row_mask:0xf bank_mask:0xf bound_ctrl:1
	s_bcnt1_i32_b64 s30, s[10:11]
	s_bcnt1_i32_b64 s31, s[26:27]
	v_cmp_le_u32_e64 s[6:7], s14, v146
	s_add_i32 s28, s28, s29
	v_add_u32_dpp v0, v0, v0 row_shr:8 row_mask:0xf bank_mask:0xf bound_ctrl:1
	v_cmp_le_u32_e64 s[10:11], s14, v143
	v_cmp_le_u32_e64 s[26:27], s14, v147
	s_add_i32 s30, s30, s31
	v_add_u32_dpp v0, v0, v0 row_bcast:15 row_mask:0xa bank_mask:0xf
	s_bcnt1_i32_b64 s29, s[4:5]
	s_bcnt1_i32_b64 s31, s[6:7]
	s_add_i32 s28, s28, s30
	v_add_u32_dpp v0, v0, v0 row_bcast:31 row_mask:0xc bank_mask:0xf
	s_bcnt1_i32_b64 s30, s[10:11]
	s_add_i32 s29, s29, s31
	s_bcnt1_i32_b64 s31, s[26:27]
	s_add_i32 s28, s28, s29
	s_add_i32 s30, s30, s31
	v_readlane_b32 s24, v0, 63
	s_add_i32 s28, s28, s30
	s_add_i32 s24, s24, s28
	s_cmp_lg_u32 s21, 2
	s_cbranch_scc1 .Lsqa_disp
	s_cmp_lg_u32 s99, 0
	s_cbranch_scc1 .Lsqa_st2
	s_cmpk_eq_i32 s24, 0x100
	s_cbranch_scc1 .Lsqa_exact
	v_cvt_f32_u32_e32 v191, s24
	s_cmpk_gt_i32 s24, 0x100
	s_cselect_b64 vcc, -1, 0
	v_max_f32_e32 v191, 0.5, v191
	s_cselect_b32 s13, s14, s13
	s_cselect_b32 s12, s12, s14
	v_log_f32_e32 v191, v191
	s_cselect_b32 s98, s24, s98
	s_cselect_b32 s15, s15, s24
	s_cselect_b32 s26, 1, 2
	v_cndmask_b32_e32 v192, v192, v88, vcc
	v_cndmask_b32_e32 v193, v88, v193, vcc
	s_cmp_eq_u32 s23, s26
	s_cselect_b32 s27, 0x3f400000, 1.0
	s_mov_b32 s23, s26
	s_add_i32 s22, s22, 1
	v_add_f32_e32 v0, 0xc1000b88, v191
	v_sub_f32_e32 v34, 0x41000b88, v191
	v_mul_f32_e32 v203, s27, v36
	v_mul_f32_e32 v204, s27, v35
	v_cndmask_b32_e32 v35, v204, v0, vcc
	v_cndmask_b32_e32 v36, v34, v203, vcc

; __device__ __forceinline__ int count_ge(const unsigned (&u)[64], unsigned cand, int nblk) {
;     int c0 = 0, c1 = 0;
;     const unsigned ts = __builtin_amdgcn_readfirstlane(cand);
; #pragma unroll
;     for (int B = 0; B < 2; ++B) {
;         if (B < nblk) {
; #pragma unroll
;             for (int i = 0; i < 32; i += 4) CNT4(c0, c1, ts, u[B * 32 + i], u[B * 32 + i + 1], u[B * 32 + i + 2], u[B * 32 + i + 3]);
;         }
;     }
.Lsqb_count:
	v_mov_b32_e32 v138, 0
	v_mov_b32_e32 v140, 0
	s_cmp_eq_u32 s32, 1
	s_cbranch_scc1 .Lsqb_red
	v_cmp_le_u32_e64 s[4:5], s14, v111
	v_cmp_le_u32_e64 s[6:7], s14, v115
	v_cmp_le_u32_e64 s[10:11], s14, v112
	v_cmp_le_u32_e64 s[26:27], s14, v116
	v_addc_co_u32_e64 v138, s[28:29], 0, v138, s[4:5]
	v_addc_co_u32_e64 v140, s[30:31], 0, v140, s[6:7]
	v_addc_co_u32_e64 v138, s[28:29], 0, v138, s[10:11]
	v_addc_co_u32_e64 v140, s[30:31], 0, v140, s[26:27]
	v_cmp_le_u32_e64 s[4:5], s14, v117
	v_cmp_le_u32_e64 s[6:7], s14, v119
	v_cmp_le_u32_e64 s[10:11], s14, v118
	v_cmp_le_u32_e64 s[26:27], s14, v121
	v_addc_co_u32_e64 v138, s[28:29], 0, v138, s[4:5]
	v_addc_co_u32_e64 v140, s[30:31], 0, v140, s[6:7]
	v_addc_co_u32_e64 v138, s[28:29], 0, v138, s[10:11]
	v_addc_co_u32_e64 v140, s[30:31], 0, v140, s[26:27]
	s_cmp_eq_u32 s32, 2
	s_cbranch_scc1 .Lsqb_red
	v_cmp_le_u32_e64 s[4:5], s14, v120
	v_cmp_le_u32_e64 s[6:7], s14, v123
	v_cmp_le_u32_e64 s[10:11], s14, v122
	v_cmp_le_u32_e64 s[26:27], s14, v124
	v_addc_co_u32_e64 v138, s[28:29], 0, v138, s[4:5]
	v_addc_co_u32_e64 v140, s[30:31], 0, v140, s[6:7]
	v_addc_co_u32_e64 v138, s[28:29], 0, v138, s[10:11]
	v_addc_co_u32_e64 v140, s[30:31], 0, v140, s[26:27]
	v_cmp_le_u32_e64 s[4:5], s14, v125
	v_cmp_le_u32_e64 s[6:7], s14, v127
	v_cmp_le_u32_e64 s[10:11], s14, v126
	v_cmp_le_u32_e64 s[26:27], s14, v128
	v_addc_co_u32_e64 v138, s[28:29], 0, v138, s[4:5]
	v_addc_co_u32_e64 v140, s[30:31], 0, v140, s[6:7]
	v_addc_co_u32_e64 v138, s[28:29], 0, v138, s[10:11]
	v_addc_co_u32_e64 v140, s[30:31], 0, v140, s[26:27]
	v_cmp_le_u32_e64 s[4:5], s14, v129
	v_cmp_le_u32_e64 s[6:7], s14, v131
	v_cmp_le_u32_e64 s[10:11], s14, v130
	v_cmp_le_u32_e64 s[26:27], s14, v132
	v_addc_co_u32_e64 v138, s[28:29], 0, v138, s[4:5]
	v_addc_co_u32_e64 v140, s[30:31], 0, v140, s[6:7]
	v_addc_co_u32_e64 v138, s[28:29], 0, v138, s[10:11]
	v_addc_co_u32_e64 v140, s[30:31], 0, v140, s[26:27]
	v_cmp_le_u32_e64 s[4:5], s14, v133
	v_cmp_le_u32_e64 s[6:7], s14, v134
	v_cmp_le_u32_e64 s[10:11], s14, v136
	v_cmp_le_u32_e64 s[26:27], s14, v137
	v_addc_co_u32_e64 v138, s[28:29], 0, v138, s[4:5]
	v_addc_co_u32_e64 v140, s[30:31], 0, v140, s[6:7]
	v_addc_co_u32_e64 v138, s[28:29], 0, v138, s[10:11]
	v_addc_co_u32_e64 v140, s[30:31], 0, v140, s[26:27]
	s_cmp_eq_u32 s32, 3
	s_cbranch_scc1 .Lsqb_red
	v_cmp_le_u32_e64 s[4:5], s14, v46
	v_cmp_le_u32_e64 s[6:7], s14, v48
	v_cmp_le_u32_e64 s[10:11], s14, v47
	v_cmp_le_u32_e64 s[26:27], s14, v49
	v_addc_co_u32_e64 v138, s[28:29], 0, v138, s[4:5]
	v_addc_co_u32_e64 v140, s[30:31], 0, v140, s[6:7]
	v_addc_co_u32_e64 v138, s[28:29], 0, v138, s[10:11]
	v_addc_co_u32_e64 v140, s[30:31], 0, v140, s[26:27]
	v_cmp_le_u32_e64 s[4:5], s14, v42
	v_cmp_le_u32_e64 s[6:7], s14, v50
	v_cmp_le_u32_e64 s[10:11], s14, v43
	v_cmp_le_u32_e64 s[26:27], s14, v44
	v_addc_co_u32_e64 v138, s[28:29], 0, v138, s[4:5]
	v_addc_co_u32_e64 v140, s[30:31], 0, v140, s[6:7]
	v_addc_co_u32_e64 v138, s[28:29], 0, v138, s[10:11]
	v_addc_co_u32_e64 v140, s[30:31], 0, v140, s[26:27]
	s_cmp_eq_u32 s32, 4
	s_cbranch_scc1 .Lsqb_red
	v_cmp_le_u32_e64 s[4:5], s14, v38
	v_cmp_le_u32_e64 s[6:7], s14, v45
	v_cmp_le_u32_e64 s[10:11], s14, v39
	v_cmp_le_u32_e64 s[26:27], s14, v40
	v_addc_co_u32_e64 v138, s[28:29], 0, v138, s[4:5]
	v_addc_co_u32_e64 v140, s[30:31], 0, v140, s[6:7]
	v_addc_co_u32_e64 v138, s[28:29], 0, v138, s[10:11]
	v_addc_co_u32_e64 v140, s[30:31], 0, v140, s[26:27]
	v_cmp_le_u32_e64 s[4:5], s14, v41
	v_cmp_le_u32_e64 s[6:7], s14, v52
	v_cmp_le_u32_e64 s[10:11], s14, v51
	v_cmp_le_u32_e64 s[26:27], s14, v54
	v_addc_co_u32_e64 v138, s[28:29], 0, v138, s[4:5]
	v_addc_co_u32_e64 v140, s[30:31], 0, v140, s[6:7]
	v_addc_co_u32_e64 v138, s[28:29], 0, v138, s[10:11]
	v_addc_co_u32_e64 v140, s[30:31], 0, v140, s[26:27]
	s_cmp_eq_u32 s32, 5
	s_cbranch_scc1 .Lsqb_red
	v_cmp_le_u32_e64 s[4:5], s14, v53
	v_cmp_le_u32_e64 s[6:7], s14, v56
	v_cmp_le_u32_e64 s[10:11], s14, v55
	v_cmp_le_u32_e64 s[26:27], s14, v57
	v_addc_co_u32_e64 v138, s[28:29], 0, v138, s[4:5]
	v_addc_co_u32_e64 v140, s[30:31], 0, v140, s[6:7]
	v_addc_co_u32_e64 v138, s[28:29], 0, v138, s[10:11]
	v_addc_co_u32_e64 v140, s[30:31], 0, v140, s[26:27]
	v_cmp_le_u32_e64 s[4:5], s14, v58
	v_cmp_le_u32_e64 s[6:7], s14, v60
	v_cmp_le_u32_e64 s[10:11], s14, v59
	v_cmp_le_u32_e64 s[26:27], s14, v61
	v_addc_co_u32_e64 v138, s[28:29], 0, v138, s[4:5]
	v_addc_co_u32_e64 v140, s[30:31], 0, v140, s[6:7]
	v_addc_co_u32_e64 v138, s[28:29], 0, v138, s[10:11]
	v_addc_co_u32_e64 v140, s[30:31], 0, v140, s[26:27]
	v_cmp_le_u32_e64 s[4:5], s14, v62
	v_cmp_le_u32_e64 s[6:7], s14, v64
	v_cmp_le_u32_e64 s[10:11], s14, v63
	v_cmp_le_u32_e64 s[26:27], s14, v65
	v_addc_co_u32_e64 v138, s[28:29], 0, v138, s[4:5]
	v_addc_co_u32_e64 v140, s[30:31], 0, v140, s[6:7]
	v_addc_co_u32_e64 v138, s[28:29], 0, v138, s[10:11]
	v_addc_co_u32_e64 v140, s[30:31], 0, v140, s[26:27]
	v_cmp_le_u32_e64 s[4:5], s14, v72
	v_cmp_le_u32_e64 s[6:7], s14, v73
	v_cmp_le_u32_e64 s[10:11], s14, v74
	v_cmp_le_u32_e64 s[26:27], s14, v75
	v_addc_co_u32_e64 v138, s[28:29], 0, v138, s[4:5]
	v_addc_co_u32_e64 v140, s[30:31], 0, v140, s[6:7]
	v_addc_co_u32_e64 v138, s[28:29], 0, v138, s[10:11]
	v_addc_co_u32_e64 v140, s[30:31], 0, v140, s[26:27]
; __device__ __forceinline__ int wave_isum(int v) {
;     v += __builtin_amdgcn_update_dpp(0, v, 0x111, 0xf, 0xf, false);
;     v += __builtin_amdgcn_update_dpp(0, v, 0x112, 0xf, 0xf, false);
;     v += __builtin_amdgcn_update_dpp(0, v, 0x114, 0xf, 0xf, false);
;     v += __builtin_amdgcn_update_dpp(0, v, 0x118, 0xf, 0xf, false);
;     v += __builtin_amdgcn_update_dpp(0, v, 0x142, 0xa, 0xf, false);
;     v += __builtin_amdgcn_update_dpp(0, v, 0x143, 0xc, 0xf, false);
;     return __builtin_amdgcn_readlane(v, 63);
; }
; __device__ __forceinline__ void select_query(const unsigned (&u)[64], unsigned vmax, int q, int b, int lane, unsigned* MASKb) {
;     ...
;             const int c = count_ge(u, mid, nblk);
;             if (c == 256) { T = mid; exact = true; break; }
;             if (c > 256) { lo = mid; Llo = __log2f((float)c) - L256; if (last == 1) Lhi *= 0.5f; last = 1; }
;             else { hi = mid; Lhi = L256 - __log2f(fmaxf((float)c, 0.5f)); if (last == 2) Llo *= 0.5f; last = 2; }
.Lsqb_red:
	v_add_u32_e32 v138, v138, v140
	v_cmp_le_u32_e64 s[4:5], s14, v98
	v_cmp_le_u32_e64 s[6:7], s14, v107
	v_add_u32_dpp v138, v138, v138 row_shr:1 row_mask:0xf bank_mask:0xf bound_ctrl:1
	v_cmp_le_u32_e64 s[10:11], s14, v99
	v_cmp_le_u32_e64 s[26:27], s14, v108
	v_add_u32_dpp v138, v138, v138 row_shr:2 row_mask:0xf bank_mask:0xf bound_ctrl:1
	s_bcnt1_i32_b64 s28, s[4:5]
	s_bcnt1_i32_b64 s29, s[6:7]
	v_cmp_le_u32_e64 s[4:5], s14, v109
	v_add_u32_dpp v138, v138, v138 row_shr:4 row_mask:0xf bank_mask:0xf bound_ctrl:1
	s_bcnt1_i32_b64 s30, s[10:11]
	s_bcnt1_i32_b64 s31, s[26:27]
	v_cmp_le_u32_e64 s[6:7], s14, v113
	s_add_i32 s28, s28, s29
	v_add_u32_dpp v138, v138, v138 row_shr:8 row_mask:0xf bank_mask:0xf bound_ctrl:1
	v_cmp_le_u32_e64 s[10:11], s14, v110
	v_cmp_le_u32_e64 s[26:27], s14, v114
	s_add_i32 s30, s30, s31
	v_add_u32_dpp v138, v138, v138 row_bcast:15 row_mask:0xa bank_mask:0xf
	s_bcnt1_i32_b64 s29, s[4:5]
	s_bcnt1_i32_b64 s31, s[6:7]
	s_add_i32 s28, s28, s30
	v_add_u32_dpp v138, v138, v138 row_bcast:31 row_mask:0xc bank_mask:0xf
	s_bcnt1_i32_b64 s30, s[10:11]
	s_add_i32 s29, s29, s31
	s_bcnt1_i32_b64 s31, s[26:27]
	s_add_i32 s28, s28, s29
	s_add_i32 s30, s30, s31
	v_readlane_b32 s24, v138, 63
	s_add_i32 s28, s28, s30
	s_add_i32 s24, s24, s28
	s_cmp_lg_u32 s21, 2
	s_cbranch_scc1 .Lsqb_disp
	s_cmp_lg_u32 s99, 0
	s_cbranch_scc1 .Lsqb_st2
	s_cmpk_eq_i32 s24, 0x100
	s_cbranch_scc1 .Lsqb_exact
	v_cvt_f32_u32_e32 v142, s24
	s_cmpk_gt_i32 s24, 0x100
	s_cselect_b64 vcc, -1, 0
	v_max_f32_e32 v142, 0.5, v142
	s_cselect_b32 s13, s14, s13
	s_cselect_b32 s12, s12, s14
	v_log_f32_e32 v142, v142
	s_cselect_b32 s98, s24, s98
	s_cselect_b32 s15, s15, s24
	s_cselect_b32 s26, 1, 2
	v_cndmask_b32_e32 v76, v76, v146, vcc
	v_cndmask_b32_e32 v77, v146, v77, vcc
	s_cmp_eq_u32 s23, s26
	s_cselect_b32 s27, 0x3f400000, 1.0
	s_mov_b32 s23, s26
	s_add_i32 s22, s22, 1
	v_add_f32_e32 v138, 0xc1000b88, v142
	v_sub_f32_e32 v140, 0x41000b88, v142
	v_mul_f32_e32 v203, s27, v141
	v_mul_f32_e32 v204, s27, v139
	v_cndmask_b32_e32 v139, v204, v138, vcc
	v_cndmask_b32_e32 v141, v140, v203, vcc
